# attention unit prologue: the seven later fragment reads of the first score block issued together behind the first, counted lgkmcnt waits in front of each MFMA
# speedup vs baseline: 1.0023x; 1.0023x over previous
.LBB0_115:
	s_lshl_b32 s88, s0, 2
	s_add_i32 s1, s88, 0
	s_add_i32 s1, s1, 0x1d280
	v_mov_b32_e32 v0, s1
	v_mov_b32_e32 v32, v194
	ds_read_b32 v0, v0
	s_lshl_b32 s89, s0, 8
	v_readfirstlane_b32 s1, v32
	s_ashr_i32 s33, s1, 6
	s_lshl_b32 s42, s33, 5
	s_or_b32 s0, s78, s89
	s_ashr_i32 s6, s42, 31
	s_add_u32 s80, s0, s42
	s_addc_u32 s81, s79, s6
	v_mov_b32_e32 v1, s88
	s_waitcnt lgkmcnt(0)
	v_and_b32_e32 v2, -2, v0
	v_cmp_lt_i32_e32 vcc, s88, v0
	s_mul_i32 s0, s81, 0x1400
	s_mul_hi_u32 s6, s80, 0x1400
	v_cndmask_b32_e32 v0, v2, v1, vcc
	s_add_i32 s0, s6, s0
	s_mul_i32 s6, s80, 0x1400
	v_readfirstlane_b32 s8, v0
	s_add_u32 s6, s20, s6
	s_addc_u32 s7, s23, s0
	s_ashr_i32 s9, s8, 31
	s_lshl_b64 s[26:27], s[8:9], 6
	s_add_u32 s0, s26, s78
	s_addc_u32 s9, s27, s79
	s_mulk_i32 s9, 0x1400
	s_mul_hi_u32 s26, s0, 0x1400
	s_add_i32 s9, s26, s9
	s_mulk_i32 s0, 0x1400
	v_and_b32_e32 v192, 63, v32
	s_add_u32 s26, s5, s0
	s_addc_u32 s27, s96, s9
	v_mul_u32_u24_e32 v0, 0xa00, v192
	s_add_u32 s74, s68, s0
	v_lshlrev_b32_e32 v98, 1, v0
	s_addc_u32 s75, s69, s9
	v_lshl_add_u64 v[0:1], s[26:27], 0, v[98:99]
	s_lshl_b32 s26, s33, 3
	s_ashr_i32 s27, s26, 31
	v_lshl_add_u64 v[188:189], s[26:27], 1, v[0:1]
	s_lshl_b32 s0, s33, 4
	v_bfe_u32 v0, v32, 2, 4
	v_and_or_b32 v0, s0, 48, v0
	s_ashr_i32 s0, s1, 3
	s_and_b32 s26, s0, 0xffffffe0
	v_mul_u32_u24_e32 v0, 0xa00, v0
	s_ashr_i32 s27, s26, 31
	s_lshl_b32 s0, s33, 10
	v_lshlrev_b32_e32 v98, 1, v0
	v_lshlrev_b32_e32 v193, 3, v32
	s_cmp_lg_u32 0, -1
	v_lshl_add_u64 v[0:1], s[74:75], 0, v[98:99]
	v_and_b32_e32 v222, 24, v193
	s_cselect_b32 s9, 0, 0
	v_lshl_add_u64 v[0:1], s[26:27], 1, v[0:1]
	v_lshlrev_b32_e32 v98, 1, v222
	s_add_i32 s74, s0, s9
	s_mov_b32 s9, m0
	s_mov_b32 m0, s74
	s_nop 0
	global_load_lds_dwordx4 v[188:189], off
	s_mov_b32 m0, s9
	v_and_b32_e32 v220, 31, v32
	v_lshl_add_u64 v[190:191], v[0:1], 0, v[98:99]
	s_add_i32 s75, s74, 0x6000
	s_mov_b32 s9, m0
	s_mov_b32 m0, s75
	s_nop 0
	global_load_lds_dwordx4 v[190:191], off
	s_mov_b32 m0, s9
	v_lshl_add_u64 v[0:1], v[188:189], 0, s[48:49]
	s_add_i32 s9, s74, 0x2000
	s_mov_b32 s26, m0
	s_mov_b32 m0, s9
	s_nop 0
	global_load_lds_dwordx4 v[0:1], off
	s_mov_b32 m0, s26
	v_mul_u32_u24_e32 v0, 0xa00, v220
	v_bfe_u32 v221, v32, 5, 1
	v_lshlrev_b32_e32 v0, 1, v0
	v_lshl_or_b32 v0, v221, 4, v0
	global_load_dwordx4 v[116:119], v0, s[6:7]
	global_load_dwordx4 v[108:111], v0, s[6:7] offset:32
	global_load_dwordx4 v[104:107], v0, s[6:7] offset:64
	global_load_dwordx4 v[100:103], v0, s[6:7] offset:96
	s_lshl_b32 s9, s8, 9
	s_add_i32 s9, s9, 0x15000
	v_cmp_gt_u32_e64 s[6:7], 32, v192
	v_lshl_or_b32 v0, v220, 3, s9
	v_mov_b32_e32 v1, 0x1d000
	v_cndmask_b32_e64 v0, v1, v0, s[6:7]
	v_add_u32_e32 v228, 0, v0
	v_lshl_add_u64 v[0:1], v[188:189], 0, s[50:51]
	s_add_i32 s9, s74, 0x4000
	s_mov_b32 s26, m0
	s_mov_b32 m0, s9
	s_nop 0
	global_load_lds_dwordx4 v[0:1], off
	s_mov_b32 m0, s26
	s_waitcnt vmcnt(3) lgkmcnt(0)
	s_barrier
	ds_read2_b64 v[14:17], v228 offset1:32
	v_mov_b32_e32 v0, 0x3f803f80
	v_cndmask_b32_e64 v98, 0, v0, s[6:7]
	v_lshlrev_b32_e32 v20, 10, v221
	v_lshlrev_b32_e32 v21, 4, v220
	s_waitcnt lgkmcnt(0)
	v_mov_b32_e32 v96, v14
	v_mov_b32_e32 v97, v15
	v_mov_b32_e32 v0, 0x3f80
	v_add3_u32 v229, 0, v20, v21
	v_cndmask_b32_e64 v129, 0, v0, s[6:7]
	v_mov_b32_e32 v128, v98
	v_mov_b32_e32 v130, v99
	v_mov_b32_e32 v131, v99
	ds_read_b128 v[34:37], v229
	ds_read_b128 v[38:41], v229 offset:512
	ds_read_b128 v[42:45], v229 offset:2048
	ds_read_b128 v[46:49], v229 offset:2560
	ds_read_b128 v[50:53], v229 offset:4096
	ds_read_b128 v[54:57], v229 offset:4608
	ds_read_b128 v[58:61], v229 offset:6144
	v_mov_b32_e32 v18, v98
	v_mfma_f32_32x32x16_bf16 v[0:15], v[96:99], v[128:131], 0
	v_mov_b32_e32 v19, v99
	s_add_i32 s9, s89, 0x100
	s_lshr_b32 s9, s9, 6
	s_sub_i32 s76, s9, s8
	v_or_b32_e32 v227, s42, v220
	s_cmp_gt_i32 s76, 4
	v_lshlrev_b32_e32 v224, 2, v221
	v_mfma_f32_32x32x16_bf16 v[16:31], v[16:19], v[128:131], 0
	s_waitcnt vmcnt(3) lgkmcnt(6)
	v_mfma_f32_32x32x16_bf16 v[0:15], v[34:37], v[116:119], v[0:15]
	ds_read_b128 v[34:37], v229 offset:6656
	s_waitcnt lgkmcnt(6)
	v_mfma_f32_32x32x16_bf16 v[16:31], v[38:41], v[116:119], v[16:31]
	s_waitcnt vmcnt(2) lgkmcnt(5)
	v_mfma_f32_32x32x16_bf16 v[0:15], v[42:45], v[108:111], v[0:15]
	s_waitcnt lgkmcnt(4)
	v_mfma_f32_32x32x16_bf16 v[16:31], v[46:49], v[108:111], v[16:31]
	s_waitcnt vmcnt(1) lgkmcnt(3)
	v_mfma_f32_32x32x16_bf16 v[0:15], v[50:53], v[104:107], v[0:15]
	s_waitcnt lgkmcnt(2)
	v_mfma_f32_32x32x16_bf16 v[16:31], v[54:57], v[104:107], v[16:31]
	s_waitcnt vmcnt(0) lgkmcnt(1)
	v_mfma_f32_32x32x16_bf16 v[0:15], v[58:61], v[100:103], v[0:15]
	s_waitcnt lgkmcnt(0)
	v_mfma_f32_32x32x16_bf16 v[16:31], v[34:37], v[100:103], v[16:31]
	s_nop 15
	s_nop 7
	s_cbranch_scc1 .LBB0_117
	s_lshl_b32 s9, s76, 6
	v_subrev_u32_e32 v33, s9, v224
	v_add_u32_e32 v35, 0x120, v33
	v_add_u32_e32 v34, 0x100, v33
	v_cmp_le_i32_e32 vcc, v35, v227
	s_nop 5
	v_cndmask_b32_e32 v16, v211, v16, vcc
	v_cmp_lt_i32_e32 vcc, v34, v227
	s_nop 1
	v_cndmask_b32_e32 v1, v211, v1, vcc
	v_cmp_le_i32_e32 vcc, v34, v227
	v_add_u32_e32 v34, 0x121, v33
	s_nop 0
	v_cndmask_b32_e32 v0, v211, v0, vcc
	v_cmp_le_i32_e32 vcc, v34, v227
	v_add_u32_e32 v34, 0x102, v33
	s_nop 0
	v_cndmask_b32_e32 v17, v211, v17, vcc
	v_cmp_le_i32_e32 vcc, v34, v227
	v_add_u32_e32 v34, 0x122, v33
	s_nop 0
	v_cndmask_b32_e32 v2, v211, v2, vcc
	v_cmp_le_i32_e32 vcc, v34, v227
	v_add_u32_e32 v34, 0x103, v33
	s_nop 0
	v_cndmask_b32_e32 v18, v211, v18, vcc
	v_cmp_le_i32_e32 vcc, v34, v227
	v_add_u32_e32 v34, 0x123, v33
	s_nop 0
	v_cndmask_b32_e32 v3, v211, v3, vcc
	v_cmp_le_i32_e32 vcc, v34, v227
	v_add_u32_e32 v34, 0x108, v33
	s_nop 0
	v_cndmask_b32_e32 v19, v211, v19, vcc
	v_cmp_le_i32_e32 vcc, v34, v227
	v_add_u32_e32 v34, 0x128, v33
	s_nop 0
	v_cndmask_b32_e32 v4, v211, v4, vcc
	v_cmp_le_i32_e32 vcc, v34, v227
	v_add_u32_e32 v34, 0x109, v33
	s_nop 0
	v_cndmask_b32_e32 v20, v211, v20, vcc
	v_cmp_le_i32_e32 vcc, v34, v227
	v_add_u32_e32 v34, 0x129, v33
	s_nop 0
	v_cndmask_b32_e32 v5, v211, v5, vcc
	v_cmp_le_i32_e32 vcc, v34, v227
	v_add_u32_e32 v34, 0x10a, v33
	s_nop 0
	v_cndmask_b32_e32 v21, v211, v21, vcc
	v_cmp_le_i32_e32 vcc, v34, v227
	v_add_u32_e32 v34, 0x12a, v33
	s_nop 0
	v_cndmask_b32_e32 v6, v211, v6, vcc
	v_cmp_le_i32_e32 vcc, v34, v227
	v_add_u32_e32 v34, 0x10b, v33
	s_nop 0
	v_cndmask_b32_e32 v22, v211, v22, vcc
	v_cmp_le_i32_e32 vcc, v34, v227
	v_add_u32_e32 v34, 0x12b, v33
	s_nop 0
	v_cndmask_b32_e32 v7, v211, v7, vcc
	v_cmp_le_i32_e32 vcc, v34, v227
	v_add_u32_e32 v34, 0x110, v33
	s_nop 0
	v_cndmask_b32_e32 v23, v211, v23, vcc
	v_cmp_le_i32_e32 vcc, v34, v227
	v_add_u32_e32 v34, 0x130, v33
	s_nop 0
	v_cndmask_b32_e32 v8, v211, v8, vcc
	v_cmp_le_i32_e32 vcc, v34, v227
	v_add_u32_e32 v34, 0x111, v33
	s_nop 0
	v_cndmask_b32_e32 v24, v211, v24, vcc
	v_cmp_le_i32_e32 vcc, v34, v227
	v_add_u32_e32 v34, 0x131, v33
	s_nop 0
	v_cndmask_b32_e32 v9, v211, v9, vcc
	v_cmp_le_i32_e32 vcc, v34, v227
	v_add_u32_e32 v34, 0x112, v33
	s_nop 0
	v_cndmask_b32_e32 v25, v211, v25, vcc
	v_cmp_le_i32_e32 vcc, v34, v227
	v_add_u32_e32 v34, 0x132, v33
	s_nop 0
	v_cndmask_b32_e32 v10, v211, v10, vcc
	v_cmp_le_i32_e32 vcc, v34, v227
	v_add_u32_e32 v34, 0x113, v33
	s_nop 0
	v_cndmask_b32_e32 v26, v211, v26, vcc
	v_cmp_le_i32_e32 vcc, v34, v227
	v_add_u32_e32 v34, 0x133, v33
	s_nop 0
	v_cndmask_b32_e32 v11, v211, v11, vcc
	v_cmp_le_i32_e32 vcc, v34, v227
	v_add_u32_e32 v34, 0x118, v33
	s_nop 0
	v_cndmask_b32_e32 v27, v211, v27, vcc
	v_cmp_le_i32_e32 vcc, v34, v227
	v_add_u32_e32 v34, 0x138, v33
	s_nop 0
	v_cndmask_b32_e32 v12, v211, v12, vcc
	v_cmp_le_i32_e32 vcc, v34, v227
	v_add_u32_e32 v34, 0x119, v33
	s_nop 0
	v_cndmask_b32_e32 v28, v211, v28, vcc
	v_cmp_le_i32_e32 vcc, v34, v227
	v_add_u32_e32 v34, 0x139, v33
	s_nop 0
	v_cndmask_b32_e32 v13, v211, v13, vcc
	v_cmp_le_i32_e32 vcc, v34, v227
	v_add_u32_e32 v34, 0x11a, v33
	s_nop 0
	v_cndmask_b32_e32 v29, v211, v29, vcc
	v_cmp_le_i32_e32 vcc, v34, v227
	v_add_u32_e32 v34, 0x13a, v33
	s_nop 0
	v_cndmask_b32_e32 v14, v211, v14, vcc
	v_cmp_le_i32_e32 vcc, v34, v227
	v_add_u32_e32 v34, 0x11b, v33
	v_add_u32_e32 v33, 0x13b, v33
	v_cndmask_b32_e32 v30, v211, v30, vcc
	v_cmp_le_i32_e32 vcc, v34, v227
	s_nop 1
	v_cndmask_b32_e32 v15, v211, v15, vcc
	v_cmp_le_i32_e32 vcc, v33, v227
	s_nop 1
	v_cndmask_b32_e32 v31, v211, v31, vcc
